# v32 plus hand rewrites: J-phase gate-weight load (32 loads in flight instead of 2) and M3 V-tile staging (8 loads in flight instead of 1)
# speedup vs baseline: 1.0028x; 1.0010x over previous
.LBB0_1034:
	s_or_b64 exec, exec, s[8:9]
	s_add_u32 s62, s88, 0xee19000
	s_addc_u32 s63, s89, 0
	s_lshl_b32 s8, s96, 2
	v_readlane_b32 s9, v253, 16
	s_add_i32 s8, s9, s8
	s_lshl_b32 s10, s8, 3
	s_and_b32 s55, s10, 0x7fffffc0
	v_readlane_b32 s10, v253, 19
	v_lshlrev_b32_e32 v12, 4, v1
	s_and_b32 s9, s8, 7
	v_add_u32_e32 v7, s10, v1
	v_ashrrev_i32_e32 v10, 4, v7
	v_and_b32_e32 v82, 0xf0, v12
	v_readlane_b32 s10, v253, 18
	v_add_u32_e32 v2, s55, v10
	v_mov_b64_e32 v[8:9], s[62:63]
	v_add_u32_e32 v6, s10, v82
	v_mad_i64_i32 v[2:3], s[10:11], v2, s83, v[8:9]
	s_lshl_b32 s70, s9, 8
	v_lshl_add_u64 v[2:3], v[2:3], 0, s[70:71]
	v_lshl_add_u64 v[2:3], v[2:3], 0, v[82:83]
	s_barrier
	s_mov_b64 s[84:85], 0x18000
	global_load_dwordx4 v[180:183], v[2:3], off offset:2048
	v_lshl_add_u64 v[2:3], v[2:3], 0, s[84:85]
	global_load_dwordx4 v[184:187], v[2:3], off offset:2048
	v_lshl_add_u64 v[2:3], v[2:3], 0, s[84:85]
	global_load_dwordx4 v[188:191], v[2:3], off offset:2048
	v_lshl_add_u64 v[2:3], v[2:3], 0, s[84:85]
	global_load_dwordx4 v[192:195], v[2:3], off offset:2048
	v_lshl_add_u64 v[2:3], v[2:3], 0, s[84:85]
	global_load_dwordx4 v[196:199], v[2:3], off offset:2048
	v_lshl_add_u64 v[2:3], v[2:3], 0, s[84:85]
	global_load_dwordx4 v[200:203], v[2:3], off offset:2048
	v_lshl_add_u64 v[2:3], v[2:3], 0, s[84:85]
	global_load_dwordx4 v[204:207], v[2:3], off offset:2048
	v_lshl_add_u64 v[2:3], v[2:3], 0, s[84:85]
	global_load_dwordx4 v[208:211], v[2:3], off offset:2048
	v_mad_u64_u32 v[10:11], s[10:11], v10, s5, v[6:7]
	s_lshl_b32 s54, s9, 7
	s_mov_b32 s9, s71
	s_waitcnt vmcnt(10)
	v_and_b32_e32 v138, 31, v1
	v_readlane_b32 s14, v253, 17
	s_mul_i32 s13, s8, 0x300
	s_load_dwordx2 s[64:65], s[40:41], 0x70
	v_or_b32_e32 v141, s14, v138
	s_mul_hi_u32 s12, s8, 0x300
	v_ashrrev_i32_e32 v143, 5, v1
	v_lshlrev_b32_e32 v134, 2, v143
	s_movk_i32 s61, 0x440
	v_ashrrev_i32_e32 v135, 31, v134
	s_mov_b32 s60, 0
	v_mov_b32_e32 v146, 0
	s_lshl_b64 s[10:11], s[8:9], 2
	s_add_u32 s10, s88, s10
	s_addc_u32 s11, s89, s11
	s_add_u32 s40, s88, s13
	v_lshlrev_b32_e32 v82, 2, v141
	s_addc_u32 s41, s89, s12
	s_mov_b32 s9, 0x1519d000
	s_waitcnt vmcnt(7)
	ds_write_b128 v10, v[180:183]
	s_waitcnt vmcnt(6)
	ds_write_b128 v10, v[184:187] offset:2176
	s_waitcnt vmcnt(5)
	ds_write_b128 v10, v[188:191] offset:4352
	s_waitcnt vmcnt(4)
	ds_write_b128 v10, v[192:195] offset:6528
	s_waitcnt vmcnt(3)
	ds_write_b128 v10, v[196:199] offset:8704
	s_waitcnt vmcnt(2)
	ds_write_b128 v10, v[200:203] offset:10880
	s_waitcnt vmcnt(1)
	ds_write_b128 v10, v[204:207] offset:13056
	s_waitcnt vmcnt(0)
	ds_write_b128 v10, v[208:211] offset:15232
	v_mov_b32_e32 v2, 0x1869d000
	global_load_dword v6, v2, s[10:11]
	v_lshl_add_u64 v[2:3], s[40:41], 0, v[82:83]
	s_mov_b64 s[10:11], 0x1519d000
	v_lshl_add_u64 v[4:5], v[2:3], 0, s[10:11]
	v_add_co_u32_e32 v2, vcc, s9, v2
	s_add_u32 s10, s62, s54
	s_nop 0
	v_addc_co_u32_e32 v3, vcc, 0, v3, vcc
	global_load_dword v139, v[2:3], off
	s_nop 0
	global_load_dword v2, v[4:5], off offset:512
	s_addc_u32 s11, s63, 0
	v_and_b32_e32 v82, 0x70, v12
	v_lshl_add_u64 v[132:133], s[10:11], 0, v[82:83]
	v_readlane_b32 s9, v253, 20
	s_waitcnt vmcnt(2)
	v_max_f32_e32 v3, v6, v6
	v_add_u32_e32 v20, s9, v82
	s_waitcnt vmcnt(0)
	v_max_f32_e32 v2, v2, v2
	v_max_f32_e32 v140, v3, v2
	v_sub_f32_e32 v2, v6, v140
	v_mul_f32_e32 v3, 0x3fb8aa3b, v2
	v_ashrrev_i32_e32 v2, 3, v1
	v_add_u32_e32 v142, s55, v2
	v_add_u32_e32 v16, s14, v142
	v_mad_i64_i32 v[4:5], s[10:11], v16, s83, v[132:133]
	v_add_u32_e32 v8, 8, v16
	global_load_dwordx4 v[4:7], v[4:5], off
	v_mad_i64_i32 v[8:9], s[10:11], v8, s83, v[132:133]
	v_add_u32_e32 v12, 16, v16
	global_load_dwordx4 v[8:11], v[8:9], off
	v_mad_i64_i32 v[12:13], s[10:11], v12, s83, v[132:133]
	v_add_u32_e32 v16, 24, v16
	global_load_dwordx4 v[12:15], v[12:13], off
	v_mad_i64_i32 v[16:17], s[10:11], v16, s83, v[132:133]
	global_load_dwordx4 v[16:19], v[16:17], off
	s_movk_i32 s10, 0x90
	v_mul_lo_u32 v21, v2, s10
	v_add_u32_e32 v144, v20, v21
	s_waitcnt vmcnt(3)
	ds_write_b128 v144, v[4:7]
	s_waitcnt vmcnt(2)
	ds_write_b128 v144, v[8:11] offset:1152
	s_waitcnt vmcnt(1)
	ds_write_b128 v144, v[12:15] offset:2304
	s_waitcnt vmcnt(0)
	ds_write_b128 v144, v[16:19] offset:3456
	v_exp_f32_e32 v4, v3
	v_mov_b32_e32 v3, s9
	v_mad_u32_u24 v3, v138, s10, v3
	v_lshlrev_b32_e32 v5, 4, v143
	s_waitcnt lgkmcnt(0)
	v_add_u32_e32 v145, v3, v5
	ds_read_b128 v[96:99], v145
	ds_read_b128 v[104:107], v145 offset:32
	ds_read_b128 v[108:111], v145 offset:64
	ds_read_b128 v[112:115], v145 offset:96
	s_mul_hi_u32 s9, s8, 0x5000
	s_waitcnt lgkmcnt(0)
	v_and_b32_e32 v9, 0xffff0000, v97
	v_and_b32_e32 v8, 0xffff0000, v96
	v_and_b32_e32 v13, 0xffff0000, v99
	v_and_b32_e32 v12, 0xffff0000, v98
	v_lshlrev_b32_e32 v7, 16, v97
	v_lshlrev_b32_e32 v6, 16, v96
	v_pk_mul_f32 v[8:9], v[4:5], v[8:9] op_sel_hi:[0,1]
	v_lshlrev_b32_e32 v11, 16, v99
	v_lshlrev_b32_e32 v10, 16, v98
	v_pk_mul_f32 v[12:13], v[4:5], v[12:13] op_sel_hi:[0,1]
	v_pk_mul_f32 v[6:7], v[4:5], v[6:7] op_sel_hi:[0,1]
	v_pk_mul_f32 v[10:11], v[4:5], v[10:11] op_sel_hi:[0,1]
	v_bfe_u32 v3, v13, 16, 1
	v_bfe_u32 v5, v12, 16, 1
	v_add3_u32 v5, v12, v5, s73
	v_add3_u32 v3, v13, v3, s73
	v_bfe_u32 v14, v10, 16, 1
	v_bfe_u32 v15, v11, 16, 1
	v_add3_u32 v11, v11, v15, s73
	v_add3_u32 v10, v10, v14, s73
	v_lshrrev_b32_e32 v10, 16, v10
	v_lshrrev_b32_e32 v11, 16, v11
	v_and_b32_e32 v13, 0xffff0000, v107
	v_and_b32_e32 v12, 0xffff0000, v106
	v_and_or_b32 v91, v3, s33, v11
	v_and_or_b32 v90, v5, s33, v10
	v_cvt_pk_bf16_f32 v89, v7, v9
	v_cvt_pk_bf16_f32 v88, v6, v8
	v_lshlrev_b32_e32 v7, 16, v105
	v_lshlrev_b32_e32 v6, 16, v104
	v_and_b32_e32 v9, 0xffff0000, v105
	v_and_b32_e32 v8, 0xffff0000, v104
	v_lshlrev_b32_e32 v11, 16, v107
	v_lshlrev_b32_e32 v10, 16, v106
	v_pk_mul_f32 v[12:13], v[4:5], v[12:13] op_sel_hi:[0,1]
	v_pk_mul_f32 v[6:7], v[4:5], v[6:7] op_sel_hi:[0,1]
	v_pk_mul_f32 v[8:9], v[4:5], v[8:9] op_sel_hi:[0,1]
	v_pk_mul_f32 v[10:11], v[4:5], v[10:11] op_sel_hi:[0,1]
	v_bfe_u32 v3, v13, 16, 1
	v_bfe_u32 v5, v12, 16, 1
	v_add3_u32 v5, v12, v5, s73
	v_add3_u32 v3, v13, v3, s73
	v_bfe_u32 v14, v10, 16, 1
	v_bfe_u32 v15, v11, 16, 1
	v_add3_u32 v11, v11, v15, s73
	v_add3_u32 v10, v10, v14, s73
	v_lshrrev_b32_e32 v10, 16, v10
	v_lshrrev_b32_e32 v11, 16, v11
	v_cvt_pk_bf16_f32 v85, v7, v9
	v_cvt_pk_bf16_f32 v84, v6, v8
	v_and_b32_e32 v9, 0xffff0000, v109
	v_and_b32_e32 v8, 0xffff0000, v108
	v_and_b32_e32 v13, 0xffff0000, v111
	v_and_b32_e32 v12, 0xffff0000, v110
	v_and_or_b32 v87, v3, s33, v11
	v_and_or_b32 v86, v5, s33, v10
	v_lshlrev_b32_e32 v7, 16, v109
	v_lshlrev_b32_e32 v6, 16, v108
	v_pk_mul_f32 v[8:9], v[4:5], v[8:9] op_sel_hi:[0,1]
	v_lshlrev_b32_e32 v11, 16, v111
	v_lshlrev_b32_e32 v10, 16, v110
	v_pk_mul_f32 v[12:13], v[4:5], v[12:13] op_sel_hi:[0,1]
	v_pk_mul_f32 v[6:7], v[4:5], v[6:7] op_sel_hi:[0,1]
	v_pk_mul_f32 v[10:11], v[4:5], v[10:11] op_sel_hi:[0,1]
	v_bfe_u32 v3, v13, 16, 1
	v_bfe_u32 v5, v12, 16, 1
	v_add3_u32 v5, v12, v5, s73
	v_add3_u32 v3, v13, v3, s73
	v_bfe_u32 v14, v10, 16, 1
	v_bfe_u32 v15, v11, 16, 1
	v_add3_u32 v11, v11, v15, s73
	v_add3_u32 v10, v10, v14, s73
	v_lshrrev_b32_e32 v10, 16, v10
	v_lshrrev_b32_e32 v11, 16, v11
	v_and_or_b32 v95, v3, s33, v11
	v_and_or_b32 v94, v5, s33, v10
	v_cvt_pk_bf16_f32 v93, v7, v9
	v_cvt_pk_bf16_f32 v92, v6, v8
	v_lshlrev_b32_e32 v7, 16, v113
	v_lshlrev_b32_e32 v6, 16, v112
	v_and_b32_e32 v9, 0xffff0000, v113
	v_and_b32_e32 v8, 0xffff0000, v112
	v_lshlrev_b32_e32 v11, 16, v115
	v_lshlrev_b32_e32 v10, 16, v114
	v_and_b32_e32 v13, 0xffff0000, v115
	v_and_b32_e32 v12, 0xffff0000, v114
	v_pk_mul_f32 v[6:7], v[4:5], v[6:7] op_sel_hi:[0,1]
	v_pk_mul_f32 v[8:9], v[4:5], v[8:9] op_sel_hi:[0,1]
	v_pk_mul_f32 v[10:11], v[4:5], v[10:11] op_sel_hi:[0,1]
	v_pk_mul_f32 v[4:5], v[4:5], v[12:13] op_sel_hi:[0,1]
	v_bfe_u32 v12, v4, 16, 1
	v_bfe_u32 v13, v9, 16, 1
	v_bfe_u32 v14, v8, 16, 1
	v_bfe_u32 v3, v5, 16, 1
	v_add3_u32 v8, v8, v14, s73
	v_add3_u32 v9, v9, v13, s73
	v_add3_u32 v4, v4, v12, s73
	v_bfe_u32 v12, v7, 16, 1
	v_bfe_u32 v13, v10, 16, 1
	v_bfe_u32 v14, v11, 16, 1
	v_add3_u32 v3, v5, v3, s73
	v_bfe_u32 v5, v6, 16, 1
	v_add3_u32 v11, v11, v14, s73
	v_add3_u32 v10, v10, v13, s73
	v_add3_u32 v7, v7, v12, s73
	s_mulk_i32 s8, 0x5000
	v_add3_u32 v5, v6, v5, s73
	v_lshrrev_b32_e32 v6, 16, v7
	v_lshrrev_b32_e32 v7, 16, v10
	v_lshrrev_b32_e32 v10, 16, v11
	s_add_u32 s8, s88, s8
	v_lshrrev_b32_e32 v5, 16, v5
	v_and_or_b32 v103, v3, s33, v10
	s_addc_u32 s9, s89, s9
	v_ashrrev_i32_e32 v3, 31, v2
	v_and_or_b32 v102, v4, s33, v7
	v_and_or_b32 v100, v8, s33, v5
	v_lshl_add_u64 v[4:5], s[8:9], 0, v[82:83]
	v_lshlrev_b64 v[2:3], 7, v[2:3]
	v_lshl_add_u64 v[66:67], v[4:5], 0, v[2:3]
	s_mov_b64 s[8:9], 0x1729d000
	v_lshl_add_u64 v[14:15], v[66:67], 0, s[8:9]
	s_mov_b32 s8, 0x1729e000
	v_add_co_u32_e32 v30, vcc, s8, v66
	v_and_or_b32 v101, v9, s33, v6
	s_nop 0
	v_addc_co_u32_e32 v31, vcc, 0, v67, vcc
	global_load_dwordx4 v[2:5], v[30:31], off offset:-4096
	global_load_dwordx4 v[6:9], v[14:15], off offset:1024
	global_load_dwordx4 v[10:13], v[14:15], off offset:2048
	s_nop 0
	global_load_dwordx4 v[14:17], v[14:15], off offset:3072
	s_waitcnt vmcnt(3)
	ds_write_b128 v144, v[2:5]
	s_waitcnt vmcnt(2)
	ds_write_b128 v144, v[6:9] offset:1152
	s_waitcnt vmcnt(1)
	ds_write_b128 v144, v[10:13] offset:2304
	s_waitcnt vmcnt(0)
	ds_write_b128 v144, v[14:17] offset:3456
	s_waitcnt lgkmcnt(0)
	ds_read_b128 v[2:5], v145
	ds_read_b128 v[18:21], v145 offset:32
	s_waitcnt lgkmcnt(1)
	v_mfma_f32_32x32x16_bf16 v[2:17], v[2:5], v[88:91], 0
	s_mov_b32 s8, 0x1729f000
	v_add_co_u32_e32 v46, vcc, s8, v66
	s_mov_b32 s8, 0x172a0000
	s_nop 0
	v_addc_co_u32_e32 v47, vcc, 0, v67, vcc
	v_add_co_u32_e32 v62, vcc, s8, v66
	s_waitcnt lgkmcnt(0)
	v_mfma_f32_32x32x16_bf16 v[2:17], v[18:21], v[84:87], v[2:17]
	ds_read_b128 v[18:21], v145 offset:64
	v_addc_co_u32_e32 v63, vcc, 0, v67, vcc
	s_mov_b32 s8, 0x172a1000
	v_add_co_u32_e32 v78, vcc, s8, v66
	v_cmp_lt_i32_e64 s[8:9], v134, v138
	s_waitcnt lgkmcnt(0)
	v_mfma_f32_32x32x16_bf16 v[2:17], v[18:21], v[92:95], v[2:17]
	ds_read_b128 v[18:21], v145 offset:96
	v_addc_co_u32_e32 v79, vcc, 0, v67, vcc
	v_cmp_le_i32_e32 vcc, v134, v138
	s_waitcnt lgkmcnt(0)
	v_mfma_f32_32x32x16_bf16 v[2:17], v[18:21], v[100:103], v[2:17]
	global_load_dwordx4 v[18:21], v[30:31], off
	global_load_dwordx4 v[22:25], v[30:31], off offset:1024
	global_load_dwordx4 v[26:29], v[30:31], off offset:2048
	s_nop 0
	global_load_dwordx4 v[30:33], v[30:31], off offset:3072
	s_waitcnt vmcnt(3)
	ds_write_b128 v144, v[18:21]
	s_waitcnt vmcnt(2)
	ds_write_b128 v144, v[22:25] offset:1152
	s_waitcnt vmcnt(1)
	ds_write_b128 v144, v[26:29] offset:2304
	s_waitcnt vmcnt(0)
	ds_write_b128 v144, v[30:33] offset:3456
	s_waitcnt lgkmcnt(0)
	ds_read_b128 v[18:21], v145
	ds_read_b128 v[34:37], v145 offset:32
	s_waitcnt lgkmcnt(1)
	v_mfma_f32_32x32x16_bf16 v[18:33], v[18:21], v[88:91], 0
	s_waitcnt lgkmcnt(0)
	v_mfma_f32_32x32x16_bf16 v[18:33], v[34:37], v[84:87], v[18:33]
	ds_read_b128 v[34:37], v145 offset:64
	s_waitcnt lgkmcnt(0)
	v_mfma_f32_32x32x16_bf16 v[18:33], v[34:37], v[92:95], v[18:33]
	ds_read_b128 v[34:37], v145 offset:96
	s_waitcnt lgkmcnt(0)
	v_mfma_f32_32x32x16_bf16 v[18:33], v[34:37], v[100:103], v[18:33]
	global_load_dwordx4 v[34:37], v[62:63], off offset:-4096
	global_load_dwordx4 v[38:41], v[46:47], off offset:1024
	global_load_dwordx4 v[42:45], v[46:47], off offset:2048
	s_nop 0
	global_load_dwordx4 v[46:49], v[46:47], off offset:3072
	s_waitcnt vmcnt(3)
	ds_write_b128 v144, v[34:37]
	s_waitcnt vmcnt(2)
	ds_write_b128 v144, v[38:41] offset:1152
	s_waitcnt vmcnt(1)
	ds_write_b128 v144, v[42:45] offset:2304
	s_waitcnt vmcnt(0)
	ds_write_b128 v144, v[46:49] offset:3456
	s_waitcnt lgkmcnt(0)
	ds_read_b128 v[34:37], v145
	ds_read_b128 v[50:53], v145 offset:32
	s_waitcnt lgkmcnt(1)
	v_mfma_f32_32x32x16_bf16 v[34:49], v[34:37], v[88:91], 0
	s_waitcnt lgkmcnt(0)
	v_mfma_f32_32x32x16_bf16 v[34:49], v[50:53], v[84:87], v[34:49]
	ds_read_b128 v[50:53], v145 offset:64
	s_waitcnt lgkmcnt(0)
	v_mfma_f32_32x32x16_bf16 v[34:49], v[50:53], v[92:95], v[34:49]
	ds_read_b128 v[50:53], v145 offset:96
	s_waitcnt lgkmcnt(0)
	v_mfma_f32_32x32x16_bf16 v[34:49], v[50:53], v[100:103], v[34:49]
	global_load_dwordx4 v[50:53], v[62:63], off
	global_load_dwordx4 v[54:57], v[62:63], off offset:1024
	global_load_dwordx4 v[58:61], v[62:63], off offset:2048
	s_nop 0
	global_load_dwordx4 v[62:65], v[62:63], off offset:3072
	s_waitcnt vmcnt(3)
	ds_write_b128 v144, v[50:53]
	s_waitcnt vmcnt(2)
	ds_write_b128 v144, v[54:57] offset:1152
	s_waitcnt vmcnt(1)
	ds_write_b128 v144, v[58:61] offset:2304
	s_waitcnt vmcnt(0)
	ds_write_b128 v144, v[62:65] offset:3456
	s_waitcnt lgkmcnt(0)
	ds_read_b128 v[50:53], v145
	ds_read_b128 v[68:71], v145 offset:32
	s_waitcnt lgkmcnt(1)
	v_mfma_f32_32x32x16_bf16 v[50:65], v[50:53], v[88:91], 0
	s_waitcnt lgkmcnt(0)
	v_mfma_f32_32x32x16_bf16 v[50:65], v[68:71], v[84:87], v[50:65]
	ds_read_b128 v[68:71], v145 offset:64
	s_waitcnt lgkmcnt(0)
	v_mfma_f32_32x32x16_bf16 v[50:65], v[68:71], v[92:95], v[50:65]
	ds_read_b128 v[68:71], v145 offset:96
	s_waitcnt lgkmcnt(0)
	v_mfma_f32_32x32x16_bf16 v[50:65], v[68:71], v[100:103], v[50:65]
	global_load_dwordx4 v[66:69], v[78:79], off
	global_load_dwordx4 v[70:73], v[78:79], off offset:1024
	global_load_dwordx4 v[74:77], v[78:79], off offset:2048
	s_nop 0
	global_load_dwordx4 v[78:81], v[78:79], off offset:3072
	s_waitcnt vmcnt(3)
	ds_write_b128 v144, v[66:69]
	s_waitcnt vmcnt(2)
	ds_write_b128 v144, v[70:73] offset:1152
	s_waitcnt vmcnt(1)
	ds_write_b128 v144, v[74:77] offset:2304
	s_waitcnt vmcnt(0)
	ds_write_b128 v144, v[78:81] offset:3456
	v_add_u32_e32 v66, 8, v134
	v_cmp_le_i32_e64 s[14:15], v66, v138
	v_add_u32_e32 v66, 9, v134
	v_cmp_le_i32_e64 s[16:17], v66, v138
	v_add_u32_e32 v66, 10, v134
	v_cmp_le_i32_e64 s[18:19], v66, v138
	v_add_u32_e32 v66, 11, v134
	v_cmp_le_i32_e64 s[20:21], v66, v138
	v_add_u32_e32 v66, 17, v134
	v_cmp_le_i32_e64 s[24:25], v66, v138
	v_add_u32_e32 v66, 18, v134
	v_cmp_le_i32_e64 s[26:27], v66, v138
	v_add_u32_e32 v66, 19, v134
	s_waitcnt lgkmcnt(0)
	v_cmp_le_i32_e64 s[28:29], v66, v138
	v_add_u32_e32 v66, 25, v134
	ds_read_b128 v[128:131], v145
	ds_read_b128 v[124:127], v145 offset:32
	ds_read_b128 v[120:123], v145 offset:64
	ds_read_b128 v[116:119], v145 offset:96
	v_cmp_le_i32_e64 s[34:35], v66, v138
	v_add_u32_e32 v66, 26, v134
	v_bfe_u32 v67, v1, 2, 2
	v_cmp_le_i32_e64 s[36:37], v66, v138
	v_add_u32_e32 v66, 27, v134
	v_cmp_le_i32_e64 s[38:39], v66, v138
	v_mul_lo_u32 v66, v143, s61
	v_mul_u32_u24_e32 v67, 0x110, v67
	v_readlane_b32 s61, v253, 60
	v_or_b32_e32 v70, 2, v134
	v_add_u32_e32 v68, 16, v134
	v_add3_u32 v66, s61, v66, v67
	v_lshlrev_b32_e32 v67, 1, v1
	v_and_b32_e32 v1, 3, v1
	v_and_b32_e32 v67, 32, v67
	v_lshlrev_b32_e32 v1, 3, v1
	v_add_u32_e32 v69, 24, v134
	v_cmp_le_i32_e64 s[10:11], v70, v138
	v_or_b32_e32 v70, 3, v134
	v_add3_u32 v1, v66, v67, v1
	v_lshl_add_u64 v[66:67], v[134:135], 2, s[40:41]
	s_mov_b64 s[40:41], 0x1519d160
	v_cmp_le_i32_e64 s[12:13], v70, v138
	v_cmp_le_i32_e64 s[22:23], v68, v138
	v_cmp_le_i32_e64 s[30:31], v69, v138
	v_lshl_add_u64 v[136:137], v[66:67], 0, s[40:41]
	s_mov_b32 s61, 0
	s_waitcnt lgkmcnt(0)
	s_barrier

.LBB0_1707:
	s_andn2_b64 vcc, exec, s[10:11]
	s_cbranch_vccnz .LBB0_1729
	s_load_dwordx2 s[12:13], s[0:1], 0x60
	v_lshrrev_b32_e32 v212, 4, v0
	v_and_b32_e32 v213, 15, v0
	v_mul_u32_u24_e32 v214, 0x1810, v212
	v_add_lshl_u32 v214, v214, v213, 2
	v_lshlrev_b32_e32 v215, 13, v213
	v_lshl_add_u32 v215, v212, 2, v215
	s_waitcnt lgkmcnt(0)
	s_add_u32 s12, s12, 0x3023000
	s_addc_u32 s13, s13, 0
	global_load_dword v180, v214, s[12:13]
	s_add_u32 s12, s12, 0xc0800
	s_addc_u32 s13, s13, 0
	global_load_dword v181, v214, s[12:13]
	s_add_u32 s12, s12, 0xc0800
	s_addc_u32 s13, s13, 0
	global_load_dword v182, v214, s[12:13]
	s_add_u32 s12, s12, 0xc0800
	s_addc_u32 s13, s13, 0
	global_load_dword v183, v214, s[12:13]
	s_add_u32 s12, s12, 0xc0800
	s_addc_u32 s13, s13, 0
	global_load_dword v184, v214, s[12:13]
	s_add_u32 s12, s12, 0xc0800
	s_addc_u32 s13, s13, 0
	global_load_dword v185, v214, s[12:13]
	s_add_u32 s12, s12, 0xc0800
	s_addc_u32 s13, s13, 0
	global_load_dword v186, v214, s[12:13]
	s_add_u32 s12, s12, 0xc0800
	s_addc_u32 s13, s13, 0
	global_load_dword v187, v214, s[12:13]
	s_add_u32 s12, s12, 0xc0800
	s_addc_u32 s13, s13, 0
	global_load_dword v188, v214, s[12:13]
	s_add_u32 s12, s12, 0xc0800
	s_addc_u32 s13, s13, 0
	global_load_dword v189, v214, s[12:13]
	s_add_u32 s12, s12, 0xc0800
	s_addc_u32 s13, s13, 0
	global_load_dword v190, v214, s[12:13]
	s_add_u32 s12, s12, 0xc0800
	s_addc_u32 s13, s13, 0
	global_load_dword v191, v214, s[12:13]
	s_add_u32 s12, s12, 0xc0800
	s_addc_u32 s13, s13, 0
	global_load_dword v192, v214, s[12:13]
	s_add_u32 s12, s12, 0xc0800
	s_addc_u32 s13, s13, 0
	global_load_dword v193, v214, s[12:13]
	s_add_u32 s12, s12, 0xc0800
	s_addc_u32 s13, s13, 0
	global_load_dword v194, v214, s[12:13]
	s_add_u32 s12, s12, 0xc0800
	s_addc_u32 s13, s13, 0
	global_load_dword v195, v214, s[12:13]
	s_add_u32 s12, s12, 0xc0800
	s_addc_u32 s13, s13, 0
	global_load_dword v196, v214, s[12:13]
	s_add_u32 s12, s12, 0xc0800
	s_addc_u32 s13, s13, 0
	global_load_dword v197, v214, s[12:13]
	s_add_u32 s12, s12, 0xc0800
	s_addc_u32 s13, s13, 0
	global_load_dword v198, v214, s[12:13]
	s_add_u32 s12, s12, 0xc0800
	s_addc_u32 s13, s13, 0
	global_load_dword v199, v214, s[12:13]
	s_add_u32 s12, s12, 0xc0800
	s_addc_u32 s13, s13, 0
	global_load_dword v200, v214, s[12:13]
	s_add_u32 s12, s12, 0xc0800
	s_addc_u32 s13, s13, 0
	global_load_dword v201, v214, s[12:13]
	s_add_u32 s12, s12, 0xc0800
	s_addc_u32 s13, s13, 0
	global_load_dword v202, v214, s[12:13]
	s_add_u32 s12, s12, 0xc0800
	s_addc_u32 s13, s13, 0
	global_load_dword v203, v214, s[12:13]
	s_add_u32 s12, s12, 0xc0800
	s_addc_u32 s13, s13, 0
	global_load_dword v204, v214, s[12:13]
	s_add_u32 s12, s12, 0xc0800
	s_addc_u32 s13, s13, 0
	global_load_dword v205, v214, s[12:13]
	s_add_u32 s12, s12, 0xc0800
	s_addc_u32 s13, s13, 0
	global_load_dword v206, v214, s[12:13]
	s_add_u32 s12, s12, 0xc0800
	s_addc_u32 s13, s13, 0
	global_load_dword v207, v214, s[12:13]
	s_add_u32 s12, s12, 0xc0800
	s_addc_u32 s13, s13, 0
	global_load_dword v208, v214, s[12:13]
	s_add_u32 s12, s12, 0xc0800
	s_addc_u32 s13, s13, 0
	global_load_dword v209, v214, s[12:13]
	s_add_u32 s12, s12, 0xc0800
	s_addc_u32 s13, s13, 0
	global_load_dword v210, v214, s[12:13]
	s_add_u32 s12, s12, 0xc0800
	s_addc_u32 s13, s13, 0
	global_load_dword v211, v214, s[12:13]
	s_add_u32 s12, s12, 0xc0800
	s_addc_u32 s13, s13, 0
	s_waitcnt vmcnt(31)
	ds_write_b32 v215, v180 offset:0
	s_waitcnt vmcnt(30)
	ds_write_b32 v215, v181 offset:128
	s_waitcnt vmcnt(29)
	ds_write_b32 v215, v182 offset:256
	s_waitcnt vmcnt(28)
	ds_write_b32 v215, v183 offset:384
	s_waitcnt vmcnt(27)
	ds_write_b32 v215, v184 offset:512
	s_waitcnt vmcnt(26)
	ds_write_b32 v215, v185 offset:640
	s_waitcnt vmcnt(25)
	ds_write_b32 v215, v186 offset:768
	s_waitcnt vmcnt(24)
	ds_write_b32 v215, v187 offset:896
	s_waitcnt vmcnt(23)
	ds_write_b32 v215, v188 offset:1024
	s_waitcnt vmcnt(22)
	ds_write_b32 v215, v189 offset:1152
	s_waitcnt vmcnt(21)
	ds_write_b32 v215, v190 offset:1280
	s_waitcnt vmcnt(20)
	ds_write_b32 v215, v191 offset:1408
	s_waitcnt vmcnt(19)
	ds_write_b32 v215, v192 offset:1536
	s_waitcnt vmcnt(18)
	ds_write_b32 v215, v193 offset:1664
	s_waitcnt vmcnt(17)
	ds_write_b32 v215, v194 offset:1792
	s_waitcnt vmcnt(16)
	ds_write_b32 v215, v195 offset:1920
	s_waitcnt vmcnt(15)
	ds_write_b32 v215, v196 offset:2048
	s_waitcnt vmcnt(14)
	ds_write_b32 v215, v197 offset:2176
	s_waitcnt vmcnt(13)
	ds_write_b32 v215, v198 offset:2304
	s_waitcnt vmcnt(12)
	ds_write_b32 v215, v199 offset:2432
	s_waitcnt vmcnt(11)
	ds_write_b32 v215, v200 offset:2560
	s_waitcnt vmcnt(10)
	ds_write_b32 v215, v201 offset:2688
	s_waitcnt vmcnt(9)
	ds_write_b32 v215, v202 offset:2816
	s_waitcnt vmcnt(8)
	ds_write_b32 v215, v203 offset:2944
	s_waitcnt vmcnt(7)
	ds_write_b32 v215, v204 offset:3072
	s_waitcnt vmcnt(6)
	ds_write_b32 v215, v205 offset:3200
	s_waitcnt vmcnt(5)
	ds_write_b32 v215, v206 offset:3328
	s_waitcnt vmcnt(4)
	ds_write_b32 v215, v207 offset:3456
	s_waitcnt vmcnt(3)
	ds_write_b32 v215, v208 offset:3584
	s_waitcnt vmcnt(2)
	ds_write_b32 v215, v209 offset:3712
	s_waitcnt vmcnt(1)
	ds_write_b32 v215, v210 offset:3840
	s_waitcnt vmcnt(0)
	ds_write_b32 v215, v211 offset:3968
	global_load_dword v180, v214, s[12:13]
	s_add_u32 s12, s12, 0xc0800
	s_addc_u32 s13, s13, 0
	global_load_dword v181, v214, s[12:13]
	s_add_u32 s12, s12, 0xc0800
	s_addc_u32 s13, s13, 0
	global_load_dword v182, v214, s[12:13]
	s_add_u32 s12, s12, 0xc0800
	s_addc_u32 s13, s13, 0
	global_load_dword v183, v214, s[12:13]
	s_add_u32 s12, s12, 0xc0800
	s_addc_u32 s13, s13, 0
	global_load_dword v184, v214, s[12:13]
	s_add_u32 s12, s12, 0xc0800
	s_addc_u32 s13, s13, 0
	global_load_dword v185, v214, s[12:13]
	s_add_u32 s12, s12, 0xc0800
	s_addc_u32 s13, s13, 0
	global_load_dword v186, v214, s[12:13]
	s_add_u32 s12, s12, 0xc0800
	s_addc_u32 s13, s13, 0
	global_load_dword v187, v214, s[12:13]
	s_add_u32 s12, s12, 0xc0800
	s_addc_u32 s13, s13, 0
	global_load_dword v188, v214, s[12:13]
	s_add_u32 s12, s12, 0xc0800
	s_addc_u32 s13, s13, 0
	global_load_dword v189, v214, s[12:13]
	s_add_u32 s12, s12, 0xc0800
	s_addc_u32 s13, s13, 0
	global_load_dword v190, v214, s[12:13]
	s_add_u32 s12, s12, 0xc0800
	s_addc_u32 s13, s13, 0
	global_load_dword v191, v214, s[12:13]
	s_add_u32 s12, s12, 0xc0800
	s_addc_u32 s13, s13, 0
	global_load_dword v192, v214, s[12:13]
	s_add_u32 s12, s12, 0xc0800
	s_addc_u32 s13, s13, 0
	global_load_dword v193, v214, s[12:13]
	s_add_u32 s12, s12, 0xc0800
	s_addc_u32 s13, s13, 0
	global_load_dword v194, v214, s[12:13]
	s_add_u32 s12, s12, 0xc0800
	s_addc_u32 s13, s13, 0
	global_load_dword v195, v214, s[12:13]
	s_add_u32 s12, s12, 0xc0800
	s_addc_u32 s13, s13, 0
	global_load_dword v196, v214, s[12:13]
	s_add_u32 s12, s12, 0xc0800
	s_addc_u32 s13, s13, 0
	global_load_dword v197, v214, s[12:13]
	s_add_u32 s12, s12, 0xc0800
	s_addc_u32 s13, s13, 0
	global_load_dword v198, v214, s[12:13]
	s_add_u32 s12, s12, 0xc0800
	s_addc_u32 s13, s13, 0
	global_load_dword v199, v214, s[12:13]
	s_add_u32 s12, s12, 0xc0800
	s_addc_u32 s13, s13, 0
	global_load_dword v200, v214, s[12:13]
	s_add_u32 s12, s12, 0xc0800
	s_addc_u32 s13, s13, 0
	global_load_dword v201, v214, s[12:13]
	s_add_u32 s12, s12, 0xc0800
	s_addc_u32 s13, s13, 0
	global_load_dword v202, v214, s[12:13]
	s_add_u32 s12, s12, 0xc0800
	s_addc_u32 s13, s13, 0
	global_load_dword v203, v214, s[12:13]
	s_add_u32 s12, s12, 0xc0800
	s_addc_u32 s13, s13, 0
	global_load_dword v204, v214, s[12:13]
	s_add_u32 s12, s12, 0xc0800
	s_addc_u32 s13, s13, 0
	global_load_dword v205, v214, s[12:13]
	s_add_u32 s12, s12, 0xc0800
	s_addc_u32 s13, s13, 0
	global_load_dword v206, v214, s[12:13]
	s_add_u32 s12, s12, 0xc0800
	s_addc_u32 s13, s13, 0
	global_load_dword v207, v214, s[12:13]
	s_add_u32 s12, s12, 0xc0800
	s_addc_u32 s13, s13, 0
	global_load_dword v208, v214, s[12:13]
	s_add_u32 s12, s12, 0xc0800
	s_addc_u32 s13, s13, 0
	global_load_dword v209, v214, s[12:13]
	s_add_u32 s12, s12, 0xc0800
	s_addc_u32 s13, s13, 0
	global_load_dword v210, v214, s[12:13]
	s_add_u32 s12, s12, 0xc0800
	s_addc_u32 s13, s13, 0
	global_load_dword v211, v214, s[12:13]
	s_add_u32 s12, s12, 0xc0800
	s_addc_u32 s13, s13, 0
	s_waitcnt vmcnt(31)
	ds_write_b32 v215, v180 offset:4096
	s_waitcnt vmcnt(30)
	ds_write_b32 v215, v181 offset:4224
	s_waitcnt vmcnt(29)
	ds_write_b32 v215, v182 offset:4352
	s_waitcnt vmcnt(28)
	ds_write_b32 v215, v183 offset:4480
	s_waitcnt vmcnt(27)
	ds_write_b32 v215, v184 offset:4608
	s_waitcnt vmcnt(26)
	ds_write_b32 v215, v185 offset:4736
	s_waitcnt vmcnt(25)
	ds_write_b32 v215, v186 offset:4864
	s_waitcnt vmcnt(24)
	ds_write_b32 v215, v187 offset:4992
	s_waitcnt vmcnt(23)
	ds_write_b32 v215, v188 offset:5120
	s_waitcnt vmcnt(22)
	ds_write_b32 v215, v189 offset:5248
	s_waitcnt vmcnt(21)
	ds_write_b32 v215, v190 offset:5376
	s_waitcnt vmcnt(20)
	ds_write_b32 v215, v191 offset:5504
	s_waitcnt vmcnt(19)
	ds_write_b32 v215, v192 offset:5632
	s_waitcnt vmcnt(18)
	ds_write_b32 v215, v193 offset:5760
	s_waitcnt vmcnt(17)
	ds_write_b32 v215, v194 offset:5888
	s_waitcnt vmcnt(16)
	ds_write_b32 v215, v195 offset:6016
	s_waitcnt vmcnt(15)
	ds_write_b32 v215, v196 offset:6144
	s_waitcnt vmcnt(14)
	ds_write_b32 v215, v197 offset:6272
	s_waitcnt vmcnt(13)
	ds_write_b32 v215, v198 offset:6400
	s_waitcnt vmcnt(12)
	ds_write_b32 v215, v199 offset:6528
	s_waitcnt vmcnt(11)
	ds_write_b32 v215, v200 offset:6656
	s_waitcnt vmcnt(10)
	ds_write_b32 v215, v201 offset:6784
	s_waitcnt vmcnt(9)
	ds_write_b32 v215, v202 offset:6912
	s_waitcnt vmcnt(8)
	ds_write_b32 v215, v203 offset:7040
	s_waitcnt vmcnt(7)
	ds_write_b32 v215, v204 offset:7168
	s_waitcnt vmcnt(6)
	ds_write_b32 v215, v205 offset:7296
	s_waitcnt vmcnt(5)
	ds_write_b32 v215, v206 offset:7424
	s_waitcnt vmcnt(4)
	ds_write_b32 v215, v207 offset:7552
	s_waitcnt vmcnt(3)
	ds_write_b32 v215, v208 offset:7680
	s_waitcnt vmcnt(2)
	ds_write_b32 v215, v209 offset:7808
	s_waitcnt vmcnt(1)
	ds_write_b32 v215, v210 offset:7936
	s_waitcnt vmcnt(0)
	ds_write_b32 v215, v211 offset:8064
